# v7 + mLSTM state waves: V fragments of the state update read ahead (8 tiles in v220..v253) instead of one LDS round trip per MFMA pair
# speedup vs baseline: 1.0010x; 1.0010x over previous
; #define LAS __attribute__((address_space(3)))
; #define MFMA16(a, b, c) __builtin_amdgcn_mfma_f32_16x16x32_bf16((a), (b), (c), 0, 0, 0)
; __device__ __forceinline__ void ml_out_unit(LAS unsigned char* lds, const MixBufs& B, int b, int h, int seg, int tid) {
;     ...
; #pragma unroll
;             for (int ks = 0; ks < 2; ++ks) { const f32x4 w0 = *(const LAS f32x4*)(WG + 32 * ks + 8 * g), w1 = *(const LAS f32x4*)(WG + 32 * ks + 8 * g + 4);
;                 const bf16x8 kf0 = scale_frag(frag_tr(lds + O_K, GP128, 32 * ks, 16 * (2 * wb), lane), w0, w1), kf1 = scale_frag(frag_tr(lds + O_K, GP128, 32 * ks, 16 * (2 * wb + 1), lane), w0, w1);
;                 nc[0] = MFMA16(kf0, ones_frag(), nc[0]); nc[1] = MFMA16(kf1, ones_frag(), nc[1]);
; #pragma unroll
;                 for (int vt = 0; vt < 8; ++vt) { const bf16x8 vf = frag_tr(lds + O_V, GP128, 32 * ks, 16 * vt, lane); Cc[0][vt] = MFMA16(kf0, vf, Cc[0][vt]); Cc[1][vt] = MFMA16(kf1, vf, Cc[1][vt]); } }
.LBB0_655:
	s_waitcnt lgkmcnt(0)
	s_barrier
	ds_read_b64_tr_b16 v[90:91], v169 offset:17408
	ds_read_b128 v[86:89], v194
	ds_read_b128 v[94:97], v194 offset:16
	ds_read_b64_tr_b16 v[92:93], v169 offset:18496
	ds_read_b64_tr_b16 v[98:99], v169 offset:17440
	ds_read_b64_tr_b16 v[220:221], v2 offset:34816
	ds_read_b64_tr_b16 v[222:223], v2 offset:35904
	ds_read_b64_tr_b16 v[224:225], v2 offset:34848
	ds_read_b64_tr_b16 v[226:227], v2 offset:35936
	ds_read_b64_tr_b16 v[228:229], v2 offset:34880
	ds_read_b64_tr_b16 v[230:231], v2 offset:35968
	ds_read_b64_tr_b16 v[232:233], v2 offset:34912
	ds_read_b64_tr_b16 v[234:235], v2 offset:36000
	s_waitcnt lgkmcnt(12)
	v_lshlrev_b32_e32 v100, 16, v90
	v_and_b32_e32 v101, 0xffff0000, v90
	s_waitcnt lgkmcnt(11)
	v_pk_mul_f32 v[100:101], v[86:87], v[100:101]
	s_cmp_eq_u32 s61, 0
	v_cvt_pk_bf16_f32 v90, v100, v101
	v_lshlrev_b32_e32 v100, 16, v91
	v_and_b32_e32 v101, 0xffff0000, v91
	v_pk_mul_f32 v[100:101], v[88:89], v[100:101]
	s_waitcnt lgkmcnt(8)
	v_lshlrev_b32_e32 v102, 16, v98
	v_cvt_pk_bf16_f32 v91, v100, v101
	v_lshlrev_b32_e32 v100, 16, v92
	v_and_b32_e32 v101, 0xffff0000, v92
	v_pk_mul_f32 v[100:101], v[94:95], v[100:101]
	v_and_b32_e32 v103, 0xffff0000, v98
	v_cvt_pk_bf16_f32 v92, v100, v101
	v_lshlrev_b32_e32 v100, 16, v93
	v_and_b32_e32 v101, 0xffff0000, v93
	v_pk_mul_f32 v[100:101], v[96:97], v[100:101]
	v_pk_mul_f32 v[86:87], v[86:87], v[102:103]
	v_cvt_pk_bf16_f32 v93, v100, v101
	ds_read_b64_tr_b16 v[100:101], v169 offset:18528
	ds_read_b64_tr_b16 v[236:237], v2 offset:34944
	ds_read_b64_tr_b16 v[238:239], v2 offset:36032
	ds_read_b64_tr_b16 v[242:243], v2 offset:34976
	ds_read_b64_tr_b16 v[244:245], v2 offset:36064
	ds_read_b64_tr_b16 v[246:247], v2 offset:35008
	ds_read_b64_tr_b16 v[248:249], v2 offset:36096
	ds_read_b64_tr_b16 v[250:251], v2 offset:35040
	ds_read_b64_tr_b16 v[252:253], v2 offset:36128
	v_cvt_pk_bf16_f32 v158, v86, v87
	v_lshlrev_b32_e32 v86, 16, v99
	v_and_b32_e32 v87, 0xffff0000, v99
	v_pk_mul_f32 v[86:87], v[88:89], v[86:87]
	s_cselect_b32 s22, s96, 0x11000
	v_cvt_pk_bf16_f32 v159, v86, v87
	s_waitcnt lgkmcnt(8)
	v_lshlrev_b32_e32 v86, 16, v100
	v_and_b32_e32 v87, 0xffff0000, v100
	v_pk_mul_f32 v[94:95], v[94:95], v[86:87]
	v_cvt_pk_bf16_f32 v160, v94, v95
	v_lshlrev_b32_e32 v94, 16, v101
	v_and_b32_e32 v95, 0xffff0000, v101
	v_pk_mul_f32 v[94:95], v[96:97], v[94:95]
	v_mfma_f32_16x16x32_bf16 v[114:117], v[90:93], v[220:223], 0
	v_cvt_pk_bf16_f32 v161, v94, v95
	s_nop 1
	v_mfma_f32_16x16x32_bf16 v[162:165], v[158:161], v[220:223], 0
	ds_read_b64_tr_b16 v[220:221], v2 offset:43520
	ds_read_b64_tr_b16 v[222:223], v2 offset:44608
	s_cselect_b32 s23, s97, 0x22000
	v_mfma_f32_16x16x32_bf16 v[118:121], v[90:93], v[228:231], 0
	v_mfma_f32_16x16x32_bf16 v[122:125], v[158:161], v[228:231], 0
	ds_read_b64_tr_b16 v[228:229], v2 offset:43584
	ds_read_b64_tr_b16 v[230:231], v2 offset:44672
	v_mfma_f32_16x16x32_bf16 v[126:129], v[90:93], v[232:235], 0
	v_mfma_f32_16x16x32_bf16 v[130:133], v[158:161], v[232:235], 0
	ds_read_b64_tr_b16 v[232:233], v2 offset:43616
	ds_read_b64_tr_b16 v[234:235], v2 offset:44704
	s_waitcnt lgkmcnt(12)
	v_mfma_f32_16x16x32_bf16 v[134:137], v[90:93], v[236:239], 0
	v_mfma_f32_16x16x32_bf16 v[138:141], v[158:161], v[236:239], 0
	ds_read_b64_tr_b16 v[236:237], v2 offset:43648
	ds_read_b64_tr_b16 v[238:239], v2 offset:44736
	s_waitcnt lgkmcnt(12)
	v_mfma_f32_16x16x32_bf16 v[142:145], v[90:93], v[242:245], 0
	v_mfma_f32_16x16x32_bf16 v[146:149], v[158:161], v[242:245], 0
	ds_read_b64_tr_b16 v[242:243], v2 offset:43680
	ds_read_b64_tr_b16 v[244:245], v2 offset:44768
	s_waitcnt lgkmcnt(12)
	v_mfma_f32_16x16x32_bf16 v[150:153], v[90:93], v[246:249], 0
	v_mfma_f32_16x16x32_bf16 v[154:157], v[158:161], v[246:249], 0
	ds_read_b64_tr_b16 v[246:247], v2 offset:43712
	ds_read_b64_tr_b16 v[248:249], v2 offset:44800
	ds_read_b64_tr_b16 v[212:213], v169 offset:26112
	s_waitcnt lgkmcnt(13)
	v_mfma_f32_16x16x32_bf16 v[110:113], v[90:93], v[250:253], 0
	v_mfma_f32_16x16x32_bf16 v[98:101], v[158:161], v[250:253], 0
	ds_read_b64_tr_b16 v[250:251], v2 offset:43744
	ds_read_b64_tr_b16 v[252:253], v2 offset:44832
	v_mov_b64_e32 v[88:89], s[86:87]
	v_mov_b64_e32 v[86:87], s[84:85]
	v_mfma_f32_16x16x32_bf16 v[102:105], v[90:93], v[224:227], 0
	v_mfma_f32_16x16x32_bf16 v[106:109], v[158:161], v[224:227], 0
	ds_read_b64_tr_b16 v[224:225], v2 offset:43552
	ds_read_b64_tr_b16 v[226:227], v2 offset:44640
	v_mfma_f32_16x16x32_bf16 v[94:97], v[158:161], v[86:89], 0
	ds_read_b128 v[204:207], v194 offset:128
	ds_read_b128 v[208:211], v194 offset:144
	ds_read_b64_tr_b16 v[160:161], v169 offset:27200
	s_waitcnt lgkmcnt(7)
	v_lshlrev_b32_e32 v158, 16, v212
	v_and_b32_e32 v159, 0xffff0000, v212
	v_lshlrev_b32_e32 v212, 16, v213
	v_and_b32_e32 v213, 0xffff0000, v213
	s_waitcnt lgkmcnt(2)
	v_pk_mul_f32 v[158:159], v[204:205], v[158:159]
	v_pk_mul_f32 v[212:213], v[206:207], v[212:213]
	ds_read_b64_tr_b16 v[214:215], v169 offset:26144
	ds_read_b64_tr_b16 v[216:217], v169 offset:27232
	v_cvt_pk_bf16_f32 v158, v158, v159
	v_cvt_pk_bf16_f32 v159, v212, v213
	s_waitcnt lgkmcnt(2)
	v_lshlrev_b32_e32 v212, 16, v160
	v_and_b32_e32 v213, 0xffff0000, v160
	v_pk_mul_f32 v[212:213], v[208:209], v[212:213]
	v_mfma_f32_16x16x32_bf16 v[90:93], v[90:93], v[86:89], 0
	v_cvt_pk_bf16_f32 v160, v212, v213
	v_lshlrev_b32_e32 v212, 16, v161
	v_and_b32_e32 v213, 0xffff0000, v161
	v_pk_mul_f32 v[212:213], v[210:211], v[212:213]
	s_nop 0
	v_cvt_pk_bf16_f32 v161, v212, v213
	s_waitcnt lgkmcnt(1)
; #define LAS __attribute__((address_space(3)))
; #define MFMA16(a, b, c) __builtin_amdgcn_mfma_f32_16x16x32_bf16((a), (b), (c), 0, 0, 0)
; __device__ __forceinline__ u32x2 f32_to_bf4(f32x4 v) { u32x2 w; w.x = cvtpk(v[0], v[1]); w.y = cvtpk(v[2], v[3]); return w; }
; __device__ __forceinline__ void ml_out_unit(LAS unsigned char* lds, const MixBufs& B, int b, int h, int seg, int tid) {
;     ...
;             for (int ks = 0; ks < 2; ++ks) { const f32x4 w0 = *(const LAS f32x4*)(WG + 32 * ks + 8 * g), w1 = *(const LAS f32x4*)(WG + 32 * ks + 8 * g + 4);
;                 const bf16x8 kf0 = scale_frag(frag_tr(lds + O_K, GP128, 32 * ks, 16 * (2 * wb), lane), w0, w1), kf1 = scale_frag(frag_tr(lds + O_K, GP128, 32 * ks, 16 * (2 * wb + 1), lane), w0, w1);
;                 nc[0] = MFMA16(kf0, ones_frag(), nc[0]); nc[1] = MFMA16(kf1, ones_frag(), nc[1]);
; #pragma unroll
;                 for (int vt = 0; vt < 8; ++vt) { const bf16x8 vf = frag_tr(lds + O_V, GP128, 32 * ks, 16 * vt, lane); Cc[0][vt] = MFMA16(kf0, vf, Cc[0][vt]); Cc[1][vt] = MFMA16(kf1, vf, Cc[1][vt]); } }
; #pragma unroll
;             for (int kt2 = 0; kt2 < 2; ++kt2) {
; #pragma unroll
;                 for (int vt = 0; vt < 8; ++vt) { C[kt2][vt] = C[kt2][vt] * sp + Cc[kt2][vt] * sl;
;                     *(LAS u32x2*)(CTn + (16 * vt + c) * GP128 + (16 * (2 * wb + kt2) + 4 * g) * 2) = f32_to_bf4(C[kt2][vt]); }
	v_lshlrev_b32_e32 v212, 16, v214
	v_and_b32_e32 v213, 0xffff0000, v214
	v_pk_mul_f32 v[204:205], v[204:205], v[212:213]
	v_lshlrev_b32_e32 v212, 16, v215
	v_and_b32_e32 v213, 0xffff0000, v215
	v_pk_mul_f32 v[206:207], v[206:207], v[212:213]
	v_cvt_pk_bf16_f32 v204, v204, v205
	v_cvt_pk_bf16_f32 v205, v206, v207
	s_waitcnt lgkmcnt(0)
	v_lshlrev_b32_e32 v206, 16, v216
	v_and_b32_e32 v207, 0xffff0000, v216
	v_pk_mul_f32 v[206:207], v[208:209], v[206:207]
	v_lshlrev_b32_e32 v208, 16, v217
	v_and_b32_e32 v209, 0xffff0000, v217
	v_pk_mul_f32 v[216:217], v[210:211], v[208:209]
	v_cvt_pk_bf16_f32 v206, v206, v207
	v_cvt_pk_bf16_f32 v207, v216, v217
	s_waitcnt lgkmcnt(0)
	v_mfma_f32_16x16x32_bf16 v[208:211], v[158:161], v[220:223], v[114:117]
	v_mfma_f32_16x16x32_bf16 v[114:117], v[204:207], v[220:223], v[162:165]
	v_mfma_f32_16x16x32_bf16 v[212:215], v[158:161], v[224:227], v[102:105]
	v_mfma_f32_16x16x32_bf16 v[102:105], v[204:207], v[224:227], v[106:109]
	v_mfma_f32_16x16x32_bf16 v[162:165], v[158:161], v[228:231], v[118:121]
	v_mfma_f32_16x16x32_bf16 v[106:109], v[204:207], v[228:231], v[122:125]
	v_mfma_f32_16x16x32_bf16 v[216:219], v[158:161], v[232:235], v[126:129]
	v_mfma_f32_16x16x32_bf16 v[126:129], v[204:207], v[232:235], v[130:133]
	v_mfma_f32_16x16x32_bf16 v[134:137], v[158:161], v[236:239], v[134:137]
	v_mfma_f32_16x16x32_bf16 v[118:121], v[204:207], v[236:239], v[138:141]
	v_mfma_f32_16x16x32_bf16 v[138:141], v[158:161], v[242:245], v[142:145]
	v_mfma_f32_16x16x32_bf16 v[122:125], v[204:207], v[242:245], v[146:149]
	v_mfma_f32_16x16x32_bf16 v[142:145], v[158:161], v[246:249], v[150:153]
	v_mfma_f32_16x16x32_bf16 v[130:133], v[204:207], v[246:249], v[154:157]
	s_nop 2
	v_add_f32_e32 v154, v167, v180
	v_max_f32_e32 v155, v181, v181
	v_max_f32_e32 v167, v154, v155
	v_mfma_f32_16x16x32_bf16 v[150:153], v[158:161], v[250:253], v[110:113]
	s_nop 2
	v_sub_f32_e32 v111, v181, v167
	v_sub_f32_e32 v110, v154, v167
	v_mul_f32_e32 v111, 0x3fb8aa3b, v111
	v_mul_f32_e32 v110, 0x3fb8aa3b, v110
	v_mfma_f32_16x16x32_bf16 v[98:101], v[204:207], v[250:253], v[98:101]
	v_exp_f32_e32 v110, v110
	v_mfma_f32_16x16x32_bf16 v[146:149], v[158:161], v[86:89], v[90:93]
	s_nop 2
	v_exp_f32_e32 v90, v111
	v_mfma_f32_16x16x32_bf16 v[86:89], v[204:207], v[86:89], v[94:97]
	v_mul_f32_e64 v92, v90, v210
	v_mul_f32_e64 v93, v90, v211
	s_nop 0
	v_pk_mul_f32 v[94:95], v[90:91], v[208:209] op_sel_hi:[0,1]
	v_pk_fma_f32 v[76:77], v[76:77], v[110:111], v[92:93] op_sel_hi:[1,0,1]
	v_pk_fma_f32 v[74:75], v[74:75], v[110:111], v[94:95] op_sel_hi:[1,0,1]
	v_cvt_pk_bf16_f32 v95, v76, v77
	v_cvt_pk_bf16_f32 v94, v74, v75
	v_add_u32_e32 v92, s22, v202
	ds_write_b64 v92, v[94:95]
	v_pk_mul_f32 v[94:95], v[90:91], v[214:215] op_sel_hi:[0,1]
	v_pk_mul_f32 v[96:97], v[90:91], v[212:213] op_sel_hi:[0,1]
	v_pk_fma_f32 v[72:73], v[72:73], v[110:111], v[94:95] op_sel_hi:[1,0,1]
	v_pk_fma_f32 v[70:71], v[70:71], v[110:111], v[96:97] op_sel_hi:[1,0,1]
	v_cvt_pk_bf16_f32 v95, v72, v73
	v_cvt_pk_bf16_f32 v94, v70, v71
	ds_write_b64 v92, v[94:95] offset:4352
	v_pk_mul_f32 v[94:95], v[90:91], v[164:165] op_sel_hi:[0,1]
	v_pk_mul_f32 v[96:97], v[90:91], v[162:163] op_sel_hi:[0,1]
	v_pk_fma_f32 v[68:69], v[68:69], v[110:111], v[94:95] op_sel_hi:[1,0,1]
	v_pk_fma_f32 v[66:67], v[66:67], v[110:111], v[96:97] op_sel_hi:[1,0,1]
	v_cvt_pk_bf16_f32 v95, v68, v69
	v_cvt_pk_bf16_f32 v94, v66, v67
	ds_write_b64 v92, v[94:95] offset:8704
	v_pk_mul_f32 v[94:95], v[90:91], v[218:219] op_sel_hi:[0,1]
	v_pk_mul_f32 v[96:97], v[90:91], v[216:217] op_sel_hi:[0,1]
	v_pk_fma_f32 v[64:65], v[64:65], v[110:111], v[94:95] op_sel_hi:[1,0,1]
	v_pk_fma_f32 v[62:63], v[62:63], v[110:111], v[96:97] op_sel_hi:[1,0,1]
	v_cvt_pk_bf16_f32 v95, v64, v65
	v_cvt_pk_bf16_f32 v94, v62, v63
	ds_write_b64 v92, v[94:95] offset:13056
	v_pk_mul_f32 v[94:95], v[90:91], v[136:137] op_sel_hi:[0,1]
	v_pk_mul_f32 v[96:97], v[90:91], v[134:135] op_sel_hi:[0,1]
	v_pk_fma_f32 v[60:61], v[60:61], v[110:111], v[94:95] op_sel_hi:[1,0,1]
	v_pk_fma_f32 v[58:59], v[58:59], v[110:111], v[96:97] op_sel_hi:[1,0,1]
	v_cvt_pk_bf16_f32 v95, v60, v61
	v_cvt_pk_bf16_f32 v94, v58, v59
	ds_write_b64 v92, v[94:95] offset:17408
	v_pk_mul_f32 v[94:95], v[90:91], v[140:141] op_sel_hi:[0,1]
	v_pk_mul_f32 v[96:97], v[90:91], v[138:139] op_sel_hi:[0,1]
; #define LAS __attribute__((address_space(3)))
; __device__ __forceinline__ u32x2 f32_to_bf4(f32x4 v) { u32x2 w; w.x = cvtpk(v[0], v[1]); w.y = cvtpk(v[2], v[3]); return w; }
; __device__ __forceinline__ void ml_out_unit(LAS unsigned char* lds, const MixBufs& B, int b, int h, int seg, int tid) {
;     ...
;             for (int kt2 = 0; kt2 < 2; ++kt2) {
; #pragma unroll
;                 for (int vt = 0; vt < 8; ++vt) { C[kt2][vt] = C[kt2][vt] * sp + Cc[kt2][vt] * sl;
;                     *(LAS u32x2*)(CTn + (16 * vt + c) * GP128 + (16 * (2 * wb + kt2) + 4 * g) * 2) = f32_to_bf4(C[kt2][vt]); }
;                 nv[kt2] = nv[kt2] * sp + nc[kt2] * sl;
;                 if (c == 0) *(LAS f32x4*)(NVn + (16 * (2 * wb + kt2) + 4 * g) * 4) = nv[kt2]; }
;             m = mn;
;             __syncthreads();
	v_pk_fma_f32 v[56:57], v[56:57], v[110:111], v[94:95] op_sel_hi:[1,0,1]
	v_pk_fma_f32 v[54:55], v[54:55], v[110:111], v[96:97] op_sel_hi:[1,0,1]
	v_cvt_pk_bf16_f32 v95, v56, v57
	v_cvt_pk_bf16_f32 v94, v54, v55
	ds_write_b64 v92, v[94:95] offset:21760
	v_pk_mul_f32 v[94:95], v[90:91], v[144:145] op_sel_hi:[0,1]
	v_pk_mul_f32 v[96:97], v[90:91], v[142:143] op_sel_hi:[0,1]
	v_pk_fma_f32 v[52:53], v[52:53], v[110:111], v[94:95] op_sel_hi:[1,0,1]
	v_pk_fma_f32 v[50:51], v[50:51], v[110:111], v[96:97] op_sel_hi:[1,0,1]
	v_cvt_pk_bf16_f32 v95, v52, v53
	v_cvt_pk_bf16_f32 v94, v50, v51
	ds_write_b64 v92, v[94:95] offset:26112
	v_pk_mul_f32 v[94:95], v[90:91], v[152:153] op_sel_hi:[0,1]
	v_pk_mul_f32 v[96:97], v[90:91], v[150:151] op_sel_hi:[0,1]
	v_pk_fma_f32 v[48:49], v[48:49], v[110:111], v[94:95] op_sel_hi:[1,0,1]
	v_pk_fma_f32 v[46:47], v[46:47], v[110:111], v[96:97] op_sel_hi:[1,0,1]
	v_cvt_pk_bf16_f32 v95, v48, v49
	v_cvt_pk_bf16_f32 v94, v46, v47
	ds_write_b64 v92, v[94:95] offset:30464
	v_pk_mul_f32 v[94:95], v[90:91], v[148:149] op_sel_hi:[0,1]
	v_pk_mul_f32 v[96:97], v[90:91], v[146:147] op_sel_hi:[0,1]
	v_pk_fma_f32 v[44:45], v[44:45], v[110:111], v[94:95] op_sel_hi:[1,0,1]
	v_pk_fma_f32 v[42:43], v[42:43], v[110:111], v[96:97] op_sel_hi:[1,0,1]
	v_add_u32_e32 v93, s23, v192
	s_and_saveexec_b64 s[22:23], s[2:3]
	ds_write_b128 v93, v[42:45]
	s_or_b64 exec, exec, s[22:23]
	v_mov_b32_e32 v91, v90
	v_mov_b32_e32 v94, v90
	v_mov_b32_e32 v95, v90
	v_mov_b32_e32 v111, v110
	v_pk_mul_f32 v[96:97], v[94:95], v[116:117]
	v_pk_mul_f32 v[112:113], v[90:91], v[114:115]
	v_mov_b32_e32 v114, v110
	v_mov_b32_e32 v115, v110
	v_pk_fma_f32 v[40:41], v[40:41], v[114:115], v[96:97]
	v_pk_fma_f32 v[38:39], v[38:39], v[110:111], v[112:113]
	v_cvt_pk_bf16_f32 v97, v40, v41
	v_cvt_pk_bf16_f32 v96, v38, v39
	ds_write_b64 v92, v[96:97] offset:32
	v_pk_mul_f32 v[96:97], v[94:95], v[104:105]
	v_pk_mul_f32 v[102:103], v[90:91], v[102:103]
	v_pk_fma_f32 v[36:37], v[36:37], v[114:115], v[96:97]
	v_pk_fma_f32 v[34:35], v[34:35], v[110:111], v[102:103]
	v_cvt_pk_bf16_f32 v97, v36, v37
	v_cvt_pk_bf16_f32 v96, v34, v35
	ds_write_b64 v92, v[96:97] offset:4384
	v_pk_mul_f32 v[96:97], v[94:95], v[108:109]
	v_pk_mul_f32 v[102:103], v[90:91], v[106:107]
	v_pk_fma_f32 v[32:33], v[32:33], v[114:115], v[96:97]
	v_pk_fma_f32 v[30:31], v[30:31], v[110:111], v[102:103]
	v_cvt_pk_bf16_f32 v97, v32, v33
	v_cvt_pk_bf16_f32 v96, v30, v31
	ds_write_b64 v92, v[96:97] offset:8736
	v_pk_mul_f32 v[96:97], v[94:95], v[128:129]
	v_pk_mul_f32 v[102:103], v[90:91], v[126:127]
	v_pk_fma_f32 v[28:29], v[28:29], v[114:115], v[96:97]
	v_pk_fma_f32 v[26:27], v[26:27], v[110:111], v[102:103]
	v_cvt_pk_bf16_f32 v97, v28, v29
	v_cvt_pk_bf16_f32 v96, v26, v27
	ds_write_b64 v92, v[96:97] offset:13088
	v_pk_mul_f32 v[96:97], v[94:95], v[120:121]
	v_pk_mul_f32 v[102:103], v[90:91], v[118:119]
	v_pk_fma_f32 v[24:25], v[24:25], v[114:115], v[96:97]
	v_pk_fma_f32 v[22:23], v[22:23], v[110:111], v[102:103]
	v_cvt_pk_bf16_f32 v97, v24, v25
	v_cvt_pk_bf16_f32 v96, v22, v23
	ds_write_b64 v92, v[96:97] offset:17440
	v_pk_mul_f32 v[96:97], v[94:95], v[124:125]
	v_pk_mul_f32 v[102:103], v[90:91], v[122:123]
	v_pk_fma_f32 v[20:21], v[20:21], v[114:115], v[96:97]
	v_pk_fma_f32 v[18:19], v[18:19], v[110:111], v[102:103]
	v_cvt_pk_bf16_f32 v97, v20, v21
	v_cvt_pk_bf16_f32 v96, v18, v19
	ds_write_b64 v92, v[96:97] offset:21792
	v_pk_mul_f32 v[96:97], v[94:95], v[132:133]
	v_pk_mul_f32 v[102:103], v[90:91], v[130:131]
	v_pk_fma_f32 v[16:17], v[16:17], v[114:115], v[96:97]
	v_pk_fma_f32 v[14:15], v[14:15], v[110:111], v[102:103]
	v_cvt_pk_bf16_f32 v97, v16, v17
	v_cvt_pk_bf16_f32 v96, v14, v15
	ds_write_b64 v92, v[96:97] offset:26144
	v_pk_mul_f32 v[96:97], v[94:95], v[100:101]
	v_pk_mul_f32 v[98:99], v[90:91], v[98:99]
	v_pk_fma_f32 v[12:13], v[12:13], v[114:115], v[96:97]
	v_pk_fma_f32 v[10:11], v[10:11], v[110:111], v[98:99]
	v_pk_mul_f32 v[88:89], v[94:95], v[88:89]
	v_pk_mul_f32 v[86:87], v[90:91], v[86:87]
	v_cvt_pk_bf16_f32 v96, v10, v11
	v_cvt_pk_bf16_f32 v97, v12, v13
	v_pk_fma_f32 v[8:9], v[8:9], v[114:115], v[88:89]
	v_pk_fma_f32 v[6:7], v[6:7], v[110:111], v[86:87]
	ds_write_b64 v92, v[96:97] offset:30496
	s_and_saveexec_b64 s[22:23], s[2:3]
	s_cbranch_execz .LBB0_648
	ds_write_b128 v93, v[6:9] offset:64
	s_branch .LBB0_648
